# attention DMA issue block: V pieces via SGPR base + 32-bit VGPR offset (no 64-bit VALU add, M0 wait state filled by SALU)
# speedup vs baseline: 1.0062x; 1.0062x over previous
.Latt_diff_p0:
.LBB0_107:
	s_add_i32 s30, s52, 2
	s_cmp_ge_u32 s30, s21
	s_cselect_b64 s[46:47], -1, 0
	s_cbranch_scc1 .LBB0_116
	s_cmp_lt_u32 s52, 2
	s_cselect_b32 s48, s45, s43
	s_mul_i32 s55, s50, 0x2400
	s_add_i32 s56, s55, s41
	s_mov_b32 m0, s56
	v_lshl_add_u32 v244, s48, 12, v153
	global_load_lds_dwordx4 v244, s[18:19]
	s_ashr_i32 s49, s48, 31
	s_lshl_b64 s[30:31], s[48:49], 1
	s_add_i32 s55, s55, s56
	s_add_i32 m0, s55, 0x6c00
	s_add_u32 s30, s39, s30
	s_addc_u32 s31, s42, s31
	global_load_lds_dwordx4 v150, s[30:31]
	s_add_i32 m0, s55, 0x8c00
	s_and_b64 vcc, exec, s[14:15]
	global_load_lds_dwordx4 v148, s[30:31]
	s_cbranch_vccz .Latt_diff_dmax

.Latt_diff_dmax:
	s_add_i32 m0, s55, 0xac00
	s_and_b64 vcc, exec, s[8:9]
	global_load_lds_dwordx4 v146, s[30:31]
	s_cbranch_vccnz .LBB0_116
	s_add_i32 m0, s56, 0x2000
	v_lshl_add_u32 v244, s48, 12, v155
	global_load_lds_dwordx4 v244, s[18:19]
	s_branch .LBB0_116

.Latt_mla_p0:
.LBB0_178:
	s_add_i32 s30, s55, 2
	s_cmp_ge_u32 s30, s20
	s_cselect_b64 s[60:61], -1, 0
	s_cbranch_scc1 .LBB0_191
	s_cmp_lt_u32 s55, 2
	s_cselect_b32 s62, s51, s49
	s_mul_i32 s57, s52, 0x6400
	s_add_i32 s57, s57, s42
	s_mov_b32 m0, s57
	v_mad_u32_u24 v217, s62, v237, v222
	global_load_lds_dwordx4 v217, s[2:3]
	s_add_i32 m0, s57, 0x2000
	v_mad_u32_u24 v217, s62, v239, v224
	global_load_lds_dwordx4 v217, s[2:3]
	s_add_i32 m0, s57, 0x4000
	v_mad_u32_u24 v217, s62, v241, v226
	global_load_lds_dwordx4 v217, s[2:3]
	s_ashr_i32 s63, s62, 31
	s_lshl_b64 s[30:31], s[62:63], 1
	s_mul_i32 s63, s52, 0x4800
	s_add_i32 s63, s63, s42
	s_add_i32 m0, s63, 0x12c00
	s_add_u32 s30, s21, s30
	s_addc_u32 s31, s43, s31
	global_load_lds_dwordx4 v202, s[30:31]
	s_add_i32 m0, s63, 0x14c00
	s_and_b64 vcc, exec, s[18:19]
	global_load_lds_dwordx4 v200, s[30:31]
	s_cbranch_vccz .Latt_mla_dmax

.Latt_mla_dmax:
	s_add_i32 m0, s63, 0x16c00
	s_and_b64 vcc, exec, s[12:13]
	global_load_lds_dwordx4 v198, s[30:31]
	s_cbranch_vccnz .LBB0_191
	s_add_i32 m0, s57, 0x6000
	v_mad_u32_u24 v217, s62, v243, v228
	global_load_lds_dwordx4 v217, s[2:3]
	s_branch .LBB0_191
